# indexer: scan_hist zeroes the bins it has just read, the per-pass zeroing phase and its barrier are gone (3 barriers fewer per unit)
# speedup vs baseline: 1.0057x; 1.0002x over previous
; #define LAS __attribute__((address_space(3)))
; __device__ __forceinline__ void scan_hist(LAS char* lds, int shiftbits) {
;     LAS unsigned* hist = (LAS unsigned*)(lds + L_HIST); LAS unsigned* part = (LAS unsigned*)(lds + L_PART);
;     LAS unsigned* pref = (LAS unsigned*)(lds + L_PREF); LAS unsigned* kremS = (LAS unsigned*)(lds + L_KREM); LAS unsigned* neqS = (LAS unsigned*)(lds + L_NEQ);
;     const int tid = opaque_tid(), q = tid & 15, g = tid >> 4;
;     unsigned hv[8]; unsigned s = 0;
; #pragma unroll
;     for (int j = 0; j < 8; ++j) { hv[j] = hist[(8 * g + j) * 16 + q]; s += hv[j]; }
;     const unsigned krem = kremS[q];
;     part[g * 16 + q] = s;
;     __syncthreads();
;     unsigned above = 0;
; #pragma unroll
;     for (int gg = 0; gg < 32; ++gg) { const unsigned pv = part[gg * 16 + q]; above += (gg > g) ? pv : 0u; }
;     if (above < krem && krem <= above + s) {
;         unsigned cum = above; int bsel = 8 * g; unsigned hsel = 0; bool done = false;
; #pragma unroll
;         for (int j = 7; j >= 0; --j) { if (!done) { if (cum + hv[j] >= krem) { bsel = 8 * g + j; hsel = hv[j]; done = true; } else cum += hv[j]; } }
;         pref[q] = (pref[q] << shiftbits) | (unsigned)bsel; kremS[q] = krem - cum; neqS[q] = hsel;
;     }
;     __syncthreads();
.LBB0_672:
	s_waitcnt vmcnt(0) lgkmcnt(0)
	s_barrier
	s_getreg_b32 s2, hwreg(HW_REG_HW_ID, 0, 6)
	s_lshl_b32 s2, s2, 2
	s_and_b32 s2, s2, 0xfc
	s_add_i32 s2, s2, 0x20040
	v_mov_b32_e32 v2, s2
	ds_read_b32 v2, v2
	s_waitcnt lgkmcnt(0)
	v_readfirstlane_b32 s2, v2
	v_mov_b32_e32 v2, v1
	s_nop 0
	v_mbcnt_lo_u32_b32 v2, -1, v2
	v_mbcnt_hi_u32_b32 v2, -1, v2
	v_lshl_or_b32 v21, s2, 6, v2
	v_and_b32_e32 v2, 15, v2
	v_ashrrev_i32_e32 v20, 4, v21
	v_lshl_add_u32 v18, v2, 2, 0
	v_lshl_add_u32 v2, v20, 9, v18
	v_add_u32_e32 v4, 0x4000, v2
	v_mov_b32_e32 v36, v4
	ds_read2_b32 v[2:3], v4 offset1:16
	ds_read2_b32 v[6:7], v4 offset0:32 offset1:48
	ds_read2_b32 v[8:9], v4 offset0:64 offset1:80
	v_lshl_add_u32 v22, v21, 2, 0
	v_add_u32_e32 v25, 0x8000, v18
	s_waitcnt lgkmcnt(2)
	v_add_u32_e32 v5, v3, v2
	s_waitcnt lgkmcnt(1)
	v_add3_u32 v5, v5, v6, v7
	s_waitcnt lgkmcnt(0)
	v_add3_u32 v19, v5, v8, v9
	ds_read2_b32 v[4:5], v4 offset0:96 offset1:112
	ds_write2_b32 v36, v1, v1 offset1:16
	ds_write2_b32 v36, v1, v1 offset0:32 offset1:48
	ds_write2_b32 v36, v1, v1 offset0:64 offset1:80
	ds_write2_b32 v36, v1, v1 offset0:96 offset1:112
	v_ashrrev_i32_e32 v21, 31, v21
	v_cmp_gt_i32_e32 vcc, 1, v20
	s_waitcnt lgkmcnt(0)
	v_add3_u32 v24, v19, v4, v5
	ds_read_b32 v19, v18 offset:34944
	ds_write_b32 v22, v24 offset:32832
	s_waitcnt lgkmcnt(0)
	s_barrier
	ds_read2_b32 v[22:23], v25 offset0:16 offset1:32
	s_waitcnt lgkmcnt(0)
	v_and_b32_e32 v21, v21, v22
	v_cndmask_b32_e32 v22, 0, v23, vcc
	v_add_u32_e32 v21, v22, v21
	ds_read2_b32 v[22:23], v25 offset0:48 offset1:64
	v_cmp_gt_i32_e32 vcc, 2, v20
	s_waitcnt lgkmcnt(0)
	s_nop 0
	v_cndmask_b32_e32 v22, 0, v22, vcc
	v_cmp_gt_i32_e32 vcc, 3, v20
	s_nop 1
	v_cndmask_b32_e32 v23, 0, v23, vcc
	v_add3_u32 v21, v21, v22, v23
	ds_read2_b32 v[22:23], v25 offset0:80 offset1:96
	v_cmp_gt_i32_e32 vcc, 4, v20
	s_waitcnt lgkmcnt(0)
	s_nop 0
	v_cndmask_b32_e32 v22, 0, v22, vcc
	v_cmp_gt_i32_e32 vcc, 5, v20
	s_nop 1
	v_cndmask_b32_e32 v23, 0, v23, vcc
	v_add3_u32 v21, v21, v22, v23
	ds_read2_b32 v[22:23], v25 offset0:112 offset1:128
	v_cmp_gt_i32_e32 vcc, 6, v20
	s_waitcnt lgkmcnt(0)
	s_nop 0
	v_cndmask_b32_e32 v22, 0, v22, vcc
	v_cmp_gt_i32_e32 vcc, 7, v20
	s_nop 1
	v_cndmask_b32_e32 v23, 0, v23, vcc
	v_add3_u32 v21, v21, v22, v23
	ds_read2_b32 v[22:23], v25 offset0:144 offset1:160
	v_cmp_gt_i32_e32 vcc, 8, v20
	s_waitcnt lgkmcnt(0)
	s_nop 0
	v_cndmask_b32_e32 v22, 0, v22, vcc
	v_cmp_gt_i32_e32 vcc, 9, v20
	s_nop 1
	v_cndmask_b32_e32 v23, 0, v23, vcc
	v_add3_u32 v21, v21, v22, v23
	ds_read2_b32 v[22:23], v25 offset0:176 offset1:192
	v_cmp_gt_i32_e32 vcc, 10, v20
	s_waitcnt lgkmcnt(0)
	s_nop 0
	v_cndmask_b32_e32 v22, 0, v22, vcc
	v_cmp_gt_i32_e32 vcc, 11, v20
	s_nop 1
	v_cndmask_b32_e32 v23, 0, v23, vcc
	v_add3_u32 v21, v21, v22, v23
	ds_read2_b32 v[22:23], v25 offset0:208 offset1:224
	v_cmp_gt_i32_e32 vcc, 12, v20
	v_add_u32_e32 v25, 0x8400, v18
	s_waitcnt lgkmcnt(0)
	v_cndmask_b32_e32 v22, 0, v22, vcc
	v_cmp_gt_i32_e32 vcc, 13, v20
	s_nop 1
	v_cndmask_b32_e32 v23, 0, v23, vcc
	v_add3_u32 v21, v21, v22, v23
	v_add_u32_e32 v22, 0x8200, v18
	ds_read2_b32 v[22:23], v22 offset0:112 offset1:128
	v_cmp_gt_i32_e32 vcc, 14, v20
	s_waitcnt lgkmcnt(0)
	s_nop 0
	v_cndmask_b32_e32 v22, 0, v22, vcc
	v_cmp_gt_i32_e32 vcc, 15, v20
	s_nop 1
	v_cndmask_b32_e32 v23, 0, v23, vcc
	v_add3_u32 v21, v21, v22, v23
	ds_read2_b32 v[22:23], v25 offset0:16 offset1:32
	v_cmp_gt_i32_e32 vcc, 16, v20
	s_waitcnt lgkmcnt(0)
	s_nop 0
	v_cndmask_b32_e32 v22, 0, v22, vcc
	v_cmp_gt_i32_e32 vcc, 17, v20
	s_nop 1
	v_cndmask_b32_e32 v23, 0, v23, vcc
	v_add3_u32 v21, v21, v22, v23
	ds_read2_b32 v[22:23], v25 offset0:48 offset1:64
	v_cmp_gt_i32_e32 vcc, 18, v20
	s_waitcnt lgkmcnt(0)
	s_nop 0
	v_cndmask_b32_e32 v22, 0, v22, vcc
	v_cmp_gt_i32_e32 vcc, 19, v20
	s_nop 1
	v_cndmask_b32_e32 v23, 0, v23, vcc
	v_add3_u32 v21, v21, v22, v23
	ds_read2_b32 v[22:23], v25 offset0:80 offset1:96
	v_cmp_gt_i32_e32 vcc, 20, v20
	s_waitcnt lgkmcnt(0)
	s_nop 0
	v_cndmask_b32_e32 v22, 0, v22, vcc
	v_cmp_gt_i32_e32 vcc, 21, v20
	s_nop 1
	v_cndmask_b32_e32 v23, 0, v23, vcc
	v_add3_u32 v21, v21, v22, v23
	ds_read2_b32 v[22:23], v25 offset0:112 offset1:128
	v_cmp_gt_i32_e32 vcc, 22, v20
	s_waitcnt lgkmcnt(0)
	s_nop 0
	v_cndmask_b32_e32 v22, 0, v22, vcc
	v_cmp_gt_i32_e32 vcc, 23, v20
	s_nop 1
	v_cndmask_b32_e32 v23, 0, v23, vcc
	v_add3_u32 v21, v21, v22, v23
	ds_read2_b32 v[22:23], v25 offset0:144 offset1:160
	v_cmp_gt_i32_e32 vcc, 24, v20
	s_waitcnt lgkmcnt(0)
	s_nop 0
	v_cndmask_b32_e32 v22, 0, v22, vcc
	v_cmp_gt_i32_e32 vcc, 25, v20
	s_nop 1
	v_cndmask_b32_e32 v23, 0, v23, vcc
	v_add3_u32 v21, v21, v22, v23
	ds_read2_b32 v[22:23], v25 offset0:176 offset1:192
	v_cmp_gt_i32_e32 vcc, 26, v20
	s_waitcnt lgkmcnt(0)
	s_nop 0
	v_cndmask_b32_e32 v22, 0, v22, vcc
	v_cmp_gt_i32_e32 vcc, 27, v20
	s_nop 1
	v_cndmask_b32_e32 v23, 0, v23, vcc
	v_add3_u32 v21, v21, v22, v23
	ds_read2_b32 v[22:23], v25 offset0:208 offset1:224
	v_cmp_gt_i32_e32 vcc, 28, v20
	s_waitcnt lgkmcnt(0)
	s_nop 0
	v_cndmask_b32_e32 v22, 0, v22, vcc
	v_cmp_gt_i32_e32 vcc, 29, v20
	s_nop 1
	v_cndmask_b32_e32 v23, 0, v23, vcc
	v_add3_u32 v21, v21, v22, v23
	v_add_u32_e32 v22, 0x8600, v18
	ds_read2_b32 v[22:23], v22 offset0:112 offset1:128
	v_cmp_gt_i32_e32 vcc, 30, v20
	s_waitcnt lgkmcnt(0)
	s_nop 0
	v_cndmask_b32_e32 v22, 0, v22, vcc
	v_cmp_gt_i32_e32 vcc, 31, v20
	s_nop 1
	v_cndmask_b32_e32 v23, 0, v23, vcc
	v_add3_u32 v22, v21, v22, v23
	v_add_u32_e32 v21, v22, v24
	v_cmp_lt_u32_e32 vcc, v22, v19
	v_cmp_le_u32_e64 s[2:3], v19, v21
	s_and_b64 s[2:3], vcc, s[2:3]
	s_and_saveexec_b64 s[4:5], s[2:3]
	s_xor_b64 s[2:3], exec, s[4:5]
	s_cbranch_execz .LBB0_702
	v_lshlrev_b32_e32 v20, 3, v20
	v_add_u32_e32 v23, v22, v5
	v_cmp_lt_u32_e32 vcc, v23, v19
	v_or_b32_e32 v21, 7, v20
	s_mov_b64 s[4:5], -1
	s_mov_b64 s[8:9], -1
	s_and_saveexec_b64 s[6:7], vcc
	s_cbranch_execz .LBB0_677
	v_add_u32_e32 v22, v23, v4
	v_cmp_ge_u32_e32 vcc, v22, v19
	v_mov_b32_e32 v5, 0
	s_mov_b64 s[8:9], 0
	v_mov_b32_e32 v21, v20
	s_and_saveexec_b64 s[10:11], vcc
	s_mov_b64 s[8:9], exec
	v_or_b32_e32 v21, 6, v20
	v_mov_b32_e32 v5, v4
	v_mov_b32_e32 v22, v23
	s_or_b64 exec, exec, s[10:11]
	s_orn2_b64 s[8:9], s[8:9], exec

; #define SEL_HADD(idx_) __hip_atomic_fetch_add(&hist[(idx_)], 1u, __ATOMIC_RELAXED, __HIP_MEMORY_SCOPE_WORKGROUP)
; __device__ __forceinline__ void sel_unit(LAS char* lds, int b, int u, const bf16_t* QI, const bf16_t* KIDX, const float* WIDX, unsigned long long* MASK) {
;     ...
;     for (int pass = 1; pass < 4; ++pass) {
;         const int shift = 24 - 8 * pass;
;         { const int t_ = opaque_tid(); for (int i = t_; i < 4096; i += 512) hist[i] = 0u; }
;         __syncthreads();
;         const unsigned pf = pref[q16];
;         unsigned zz = 0u; asm volatile("" : "+v"(zz));
; #pragma unroll
;         for (int j = 0; j < 8; ++j) if (j < nj) {
; #pragma unroll
;             for (int kb = 0; kb < 4; ++kb)
; #pragma unroll
;                 for (int i = 0; i < 4; ++i) { const unsigned k = sc[j][kb][i] | zz; SEL_HADD((((k >> (shift + 8)) == pf) ? ((k >> shift) & 255u) * 16 : 4096u) + q16); __builtin_amdgcn_sched_barrier(0); }
.LBB0_706:
	ds_read_b32 v2, v60 offset:34880
	s_lshl_b32 s2, s21, 3
	s_sub_i32 s16, 24, s2
	v_mov_b32_e32 v3, 0
	s_sub_i32 s17, 32, s2
	s_and_b64 vcc, exec, s[22:23]
	s_cbranch_vccz .LBB0_711
	v_lshrrev_b32_e32 v5, s17, v62
	s_waitcnt lgkmcnt(0)
	v_cmp_eq_u32_e32 vcc, v5, v2
	s_cbranch_vccz .Lsel_skip_1
	v_lshrrev_b32_e32 v4, s16, v62
	v_lshlrev_b32_e32 v4, 4, v4
	v_and_b32_e32 v4, 0xff0, v4
	v_cndmask_b32_e32 v4, v203, v4, vcc
	v_lshl_add_u32 v4, v4, 2, v0
	ds_add_u32 v4, v205 offset:16384

; #define LAS __attribute__((address_space(3)))
; __device__ __forceinline__ void scan_hist(LAS char* lds, int shiftbits) {
;     LAS unsigned* hist = (LAS unsigned*)(lds + L_HIST); LAS unsigned* part = (LAS unsigned*)(lds + L_PART);
;     LAS unsigned* pref = (LAS unsigned*)(lds + L_PREF); LAS unsigned* kremS = (LAS unsigned*)(lds + L_KREM); LAS unsigned* neqS = (LAS unsigned*)(lds + L_NEQ);
;     const int tid = opaque_tid(), q = tid & 15, g = tid >> 4;
;     unsigned hv[8]; unsigned s = 0;
; #pragma unroll
;     for (int j = 0; j < 8; ++j) { hv[j] = hist[(8 * g + j) * 16 + q]; s += hv[j]; }
;     const unsigned krem = kremS[q];
;     part[g * 16 + q] = s;
;     __syncthreads();
;     unsigned above = 0;
; #pragma unroll
;     for (int gg = 0; gg < 32; ++gg) { const unsigned pv = part[gg * 16 + q]; above += (gg > g) ? pv : 0u; }
;     if (above < krem && krem <= above + s) {
;         unsigned cum = above; int bsel = 8 * g; unsigned hsel = 0; bool done = false;
; #pragma unroll
;         for (int j = 7; j >= 0; --j) { if (!done) { if (cum + hv[j] >= krem) { bsel = 8 * g + j; hsel = hv[j]; done = true; } else cum += hv[j]; } }
;         pref[q] = (pref[q] << shiftbits) | (unsigned)bsel; kremS[q] = krem - cum; neqS[q] = hsel;
;     }
;     __syncthreads();
.LBB0_719:
	s_waitcnt lgkmcnt(0)
	s_barrier
	s_getreg_b32 s16, hwreg(HW_REG_HW_ID, 0, 6)
	s_lshl_b32 s16, s16, 2
	s_and_b32 s16, s16, 0xfc
	s_add_i32 s16, s16, 0x20040
	v_mov_b32_e32 v2, s16
	ds_read_b32 v2, v2
	s_waitcnt lgkmcnt(0)
	v_readfirstlane_b32 s16, v2
	v_mov_b32_e32 v2, 0
	s_nop 0
	v_mbcnt_lo_u32_b32 v2, -1, v2
	v_mbcnt_hi_u32_b32 v2, -1, v2
	v_lshl_or_b32 v21, s16, 6, v2
	v_and_b32_e32 v2, 15, v2
	v_ashrrev_i32_e32 v20, 4, v21
	v_lshl_add_u32 v18, v2, 2, 0
	v_lshl_add_u32 v2, v20, 9, v18
	v_add_u32_e32 v4, 0x4000, v2
	v_mov_b32_e32 v36, v4
	ds_read2_b32 v[2:3], v4 offset1:16
	ds_read2_b32 v[6:7], v4 offset0:32 offset1:48
	ds_read2_b32 v[8:9], v4 offset0:64 offset1:80
	v_lshl_add_u32 v22, v21, 2, 0
	v_add_u32_e32 v25, 0x8000, v18
	s_waitcnt lgkmcnt(2)
	v_add_u32_e32 v5, v3, v2
	s_waitcnt lgkmcnt(1)
	v_add3_u32 v5, v5, v6, v7
	s_waitcnt lgkmcnt(0)
	v_add3_u32 v19, v5, v8, v9
	ds_read2_b32 v[4:5], v4 offset0:96 offset1:112
	ds_write2_b32 v36, v1, v1 offset1:16
	ds_write2_b32 v36, v1, v1 offset0:32 offset1:48
	ds_write2_b32 v36, v1, v1 offset0:64 offset1:80
	ds_write2_b32 v36, v1, v1 offset0:96 offset1:112
	v_ashrrev_i32_e32 v21, 31, v21
	v_cmp_gt_i32_e32 vcc, 1, v20
	s_waitcnt lgkmcnt(0)
	v_add3_u32 v24, v19, v4, v5
	ds_read_b32 v19, v18 offset:34944
	ds_write_b32 v22, v24 offset:32832
	s_waitcnt lgkmcnt(0)
	s_barrier
	ds_read2_b32 v[22:23], v25 offset0:16 offset1:32
	s_waitcnt lgkmcnt(0)
	v_and_b32_e32 v21, v21, v22
	v_cndmask_b32_e32 v22, 0, v23, vcc
	v_add_u32_e32 v21, v22, v21
	ds_read2_b32 v[22:23], v25 offset0:48 offset1:64
	v_cmp_gt_i32_e32 vcc, 2, v20
	s_waitcnt lgkmcnt(0)
	s_nop 0
	v_cndmask_b32_e32 v22, 0, v22, vcc
	v_cmp_gt_i32_e32 vcc, 3, v20
	s_nop 1
	v_cndmask_b32_e32 v23, 0, v23, vcc
	v_add3_u32 v21, v21, v22, v23
	ds_read2_b32 v[22:23], v25 offset0:80 offset1:96
	v_cmp_gt_i32_e32 vcc, 4, v20
	s_waitcnt lgkmcnt(0)
	s_nop 0
	v_cndmask_b32_e32 v22, 0, v22, vcc
	v_cmp_gt_i32_e32 vcc, 5, v20
	s_nop 1
	v_cndmask_b32_e32 v23, 0, v23, vcc
	v_add3_u32 v21, v21, v22, v23
	ds_read2_b32 v[22:23], v25 offset0:112 offset1:128
	v_cmp_gt_i32_e32 vcc, 6, v20
	s_waitcnt lgkmcnt(0)
	s_nop 0
	v_cndmask_b32_e32 v22, 0, v22, vcc
	v_cmp_gt_i32_e32 vcc, 7, v20
	s_nop 1
	v_cndmask_b32_e32 v23, 0, v23, vcc
	v_add3_u32 v21, v21, v22, v23
	ds_read2_b32 v[22:23], v25 offset0:144 offset1:160
	v_cmp_gt_i32_e32 vcc, 8, v20
	s_waitcnt lgkmcnt(0)
	s_nop 0
	v_cndmask_b32_e32 v22, 0, v22, vcc
	v_cmp_gt_i32_e32 vcc, 9, v20
	s_nop 1
	v_cndmask_b32_e32 v23, 0, v23, vcc
	v_add3_u32 v21, v21, v22, v23
	ds_read2_b32 v[22:23], v25 offset0:176 offset1:192
	v_cmp_gt_i32_e32 vcc, 10, v20
	s_waitcnt lgkmcnt(0)
	s_nop 0
	v_cndmask_b32_e32 v22, 0, v22, vcc
	v_cmp_gt_i32_e32 vcc, 11, v20
	s_nop 1
	v_cndmask_b32_e32 v23, 0, v23, vcc
	v_add3_u32 v21, v21, v22, v23
	ds_read2_b32 v[22:23], v25 offset0:208 offset1:224
	v_cmp_gt_i32_e32 vcc, 12, v20
	v_add_u32_e32 v25, 0x8400, v18
	s_waitcnt lgkmcnt(0)
	v_cndmask_b32_e32 v22, 0, v22, vcc
	v_cmp_gt_i32_e32 vcc, 13, v20
	s_nop 1
	v_cndmask_b32_e32 v23, 0, v23, vcc
	v_add3_u32 v21, v21, v22, v23
	v_add_u32_e32 v22, 0x8200, v18
	ds_read2_b32 v[22:23], v22 offset0:112 offset1:128
	v_cmp_gt_i32_e32 vcc, 14, v20
	s_waitcnt lgkmcnt(0)
	s_nop 0
	v_cndmask_b32_e32 v22, 0, v22, vcc
	v_cmp_gt_i32_e32 vcc, 15, v20
	s_nop 1
	v_cndmask_b32_e32 v23, 0, v23, vcc
	v_add3_u32 v21, v21, v22, v23
	ds_read2_b32 v[22:23], v25 offset0:16 offset1:32
	v_cmp_gt_i32_e32 vcc, 16, v20
	s_waitcnt lgkmcnt(0)
	s_nop 0
	v_cndmask_b32_e32 v22, 0, v22, vcc
	v_cmp_gt_i32_e32 vcc, 17, v20
	s_nop 1
	v_cndmask_b32_e32 v23, 0, v23, vcc
	v_add3_u32 v21, v21, v22, v23
	ds_read2_b32 v[22:23], v25 offset0:48 offset1:64
	v_cmp_gt_i32_e32 vcc, 18, v20
	s_waitcnt lgkmcnt(0)
	s_nop 0
	v_cndmask_b32_e32 v22, 0, v22, vcc
	v_cmp_gt_i32_e32 vcc, 19, v20
	s_nop 1
	v_cndmask_b32_e32 v23, 0, v23, vcc
	v_add3_u32 v21, v21, v22, v23
	ds_read2_b32 v[22:23], v25 offset0:80 offset1:96
	v_cmp_gt_i32_e32 vcc, 20, v20
	s_waitcnt lgkmcnt(0)
	s_nop 0
	v_cndmask_b32_e32 v22, 0, v22, vcc
	v_cmp_gt_i32_e32 vcc, 21, v20
	s_nop 1
	v_cndmask_b32_e32 v23, 0, v23, vcc
	v_add3_u32 v21, v21, v22, v23
	ds_read2_b32 v[22:23], v25 offset0:112 offset1:128
	v_cmp_gt_i32_e32 vcc, 22, v20
	s_waitcnt lgkmcnt(0)
	s_nop 0
	v_cndmask_b32_e32 v22, 0, v22, vcc
	v_cmp_gt_i32_e32 vcc, 23, v20
	s_nop 1
	v_cndmask_b32_e32 v23, 0, v23, vcc
	v_add3_u32 v21, v21, v22, v23
	ds_read2_b32 v[22:23], v25 offset0:144 offset1:160
	v_cmp_gt_i32_e32 vcc, 24, v20
	s_waitcnt lgkmcnt(0)
	s_nop 0
	v_cndmask_b32_e32 v22, 0, v22, vcc
	v_cmp_gt_i32_e32 vcc, 25, v20
	s_nop 1
	v_cndmask_b32_e32 v23, 0, v23, vcc
	v_add3_u32 v21, v21, v22, v23
	ds_read2_b32 v[22:23], v25 offset0:176 offset1:192
	v_cmp_gt_i32_e32 vcc, 26, v20
	s_waitcnt lgkmcnt(0)
	s_nop 0
	v_cndmask_b32_e32 v22, 0, v22, vcc
	v_cmp_gt_i32_e32 vcc, 27, v20
	s_nop 1
	v_cndmask_b32_e32 v23, 0, v23, vcc
	v_add3_u32 v21, v21, v22, v23
	ds_read2_b32 v[22:23], v25 offset0:208 offset1:224
	v_cmp_gt_i32_e32 vcc, 28, v20
	s_waitcnt lgkmcnt(0)
	s_nop 0
	v_cndmask_b32_e32 v22, 0, v22, vcc
	v_cmp_gt_i32_e32 vcc, 29, v20
	s_nop 1
	v_cndmask_b32_e32 v23, 0, v23, vcc
	v_add3_u32 v21, v21, v22, v23
	v_add_u32_e32 v22, 0x8600, v18
	ds_read2_b32 v[22:23], v22 offset0:112 offset1:128
	v_cmp_gt_i32_e32 vcc, 30, v20
	s_waitcnt lgkmcnt(0)
	s_nop 0
	v_cndmask_b32_e32 v22, 0, v22, vcc
	v_cmp_gt_i32_e32 vcc, 31, v20
	s_nop 1
	v_cndmask_b32_e32 v23, 0, v23, vcc
	v_add3_u32 v22, v21, v22, v23
	v_add_u32_e32 v21, v22, v24
	v_cmp_lt_u32_e32 vcc, v22, v19
	v_cmp_le_u32_e64 s[16:17], v19, v21
	s_and_b64 s[16:17], vcc, s[16:17]
	s_and_saveexec_b64 s[28:29], s[16:17]
	s_xor_b64 s[16:17], exec, s[28:29]
	s_cbranch_execz .LBB0_705
	v_lshlrev_b32_e32 v20, 3, v20
	v_add_u32_e32 v23, v22, v5
	v_cmp_lt_u32_e32 vcc, v23, v19
	v_or_b32_e32 v21, 7, v20
	s_mov_b64 s[28:29], -1
	s_mov_b64 s[74:75], -1
	s_and_saveexec_b64 s[44:45], vcc
	s_cbranch_execz .LBB0_724
	v_add_u32_e32 v22, v23, v4
	v_cmp_ge_u32_e32 vcc, v22, v19
	v_mov_b32_e32 v5, 0
	s_mov_b64 s[74:75], 0
	v_mov_b32_e32 v21, v20
	s_and_saveexec_b64 s[76:77], vcc
	s_mov_b64 s[74:75], exec
	v_or_b32_e32 v21, 6, v20
	v_mov_b32_e32 v5, v4
	v_mov_b32_e32 v22, v23
	s_or_b64 exec, exec, s[76:77]
	s_orn2_b64 s[74:75], s[74:75], exec
